# mixers queue: static XCD-aligned assignment of ret_prompt units (4 e-slices of one head on one XCD share Q/K via L2); on top of v26
# speedup vs baseline: 1.0097x; 1.0086x over previous
; #define LAS __attribute__((address_space(3)))
; __device__ __forceinline__ void phase_mixers(const Params& p, LAS unsigned char* lds, int rep) {
;   unsigned* ctr = (unsigned*)(p.ws + WS_CTL) + rep;
;   LAS unsigned* slot = (LAS unsigned*)(lds + LDS_CTL);
;   unsigned nxt = 0u;
;   if (threadIdx.x == 0) nxt = atomicAdd(ctr, 1u);
;   for (;;) {
;     __syncthreads();
;     if (threadIdx.x == 0) *slot = nxt;
;     __syncthreads();
;     const int u = (int)__builtin_amdgcn_readfirstlane(*slot);
;     if (u >= 2304) break;
;     if (threadIdx.x == 0) nxt = atomicAdd(ctr, 1u);
;     if (u < 128) mix_ret_prompt(p, lds, u);
.LBB0_176:
	s_andn2_b64 vcc, exec, s[36:37]
	s_cbranch_vccnz .LBB0_247
	s_lshl_b64 s[34:35], s[40:41], 2
	s_add_u32 s30, s24, s34
	s_addc_u32 s31, s25, s35
	v_writelane_b32 v255, s30, 48
	v_mov_b32_e32 v186, 0
	s_nop 0
	v_writelane_b32 v255, s31, 49
	s_mov_b64 s[36:37], exec
	v_readlane_b32 s34, v251, 32
	v_readlane_b32 s35, v251, 33
	s_and_b64 s[34:35], s[36:37], s[34:35]
	s_mov_b64 exec, s[34:35]
	s_cbranch_execz .LBB0_181
	s_cmpk_lg_u32 s28, 0x100
	s_cbranch_scc1 .Lq_dyn
	v_readlane_b32 s29, v255, 31
	s_nop 1
	s_cmpk_lt_u32 s29, 0x80
	s_cbranch_scc0 .Lq_dyn
	s_and_b32 s30, s29, 7
	s_lshr_b32 s31, s29, 5
	s_lshl_b32 s31, s31, 3
	s_add_i32 s30, s30, s31
	s_lshl_b32 s30, s30, 2
	s_bfe_u32 s31, s29, 0x20003
	s_add_i32 s30, s30, s31
	v_mov_b32_e32 v186, s30
	s_branch .LBB0_181
.Lq_dyn:
	s_mov_b64 s[40:41], exec
	v_mbcnt_lo_u32_b32 v0, s40, 0
	v_mbcnt_hi_u32_b32 v0, s41, v0
	v_cmp_eq_u32_e32 vcc, 0, v0
	s_and_saveexec_b64 s[38:39], vcc
	s_cbranch_execz .LBB0_180
	s_bcnt1_i32_b64 s29, s[40:41]
	v_readlane_b32 s30, v255, 48
	v_mov_b32_e32 v1, s29
	v_readlane_b32 s31, v255, 49
	s_nop 4
	global_atomic_add v1, v65, v1, s[30:31] sc0
.LBB0_180:
	s_or_b64 exec, exec, s[38:39]
	s_waitcnt vmcnt(0)
	v_readfirstlane_b32 s29, v1
	s_cmpk_eq_u32 s28, 0x100
	s_cselect_b32 s30, 0x80, 0
	s_add_i32 s29, s29, s30
	v_add_u32_e32 v186, s29, v0

; __device__ __forceinline__ void phase_mixers(const Params& p, LAS unsigned char* lds, int rep) {
;     ...
;   for (;;) {
;     __syncthreads();
;     if (threadIdx.x == 0) *slot = nxt;
;     __syncthreads();
;     const int u = (int)__builtin_amdgcn_readfirstlane(*slot);
;     if (u >= 2304) break;
;     if (threadIdx.x == 0) nxt = atomicAdd(ctr, 1u);
;     if (u < 128) mix_ret_prompt(p, lds, u);
.LBB0_190:
	s_or_b64 exec, exec, s[38:39]
	s_waitcnt vmcnt(0)
	v_readfirstlane_b32 s29, v1
	s_cmpk_eq_u32 s28, 0x100
	s_cselect_b32 s30, 0x80, 0
	s_add_i32 s29, s29, s30
	v_add_u32_e32 v186, s29, v0
	s_or_b64 exec, exec, s[36:37]
	s_cmpk_gt_i32 s42, 0x7f
	s_mov_b64 s[36:37], -1
	s_cbranch_scc1 .LBB0_193
